# v14
# speedup vs baseline: 1.0088x; 1.0057x over previous
; #define LAS __attribute__((address_space(3)))
; __device__ __forceinline__ unsigned xb_add(unsigned* p, unsigned v) { return __hip_atomic_fetch_add(p, v, __ATOMIC_RELAXED, __HIP_MEMORY_SCOPE_AGENT); }
; __device__ __forceinline__ unsigned xb_xcc_id() { return (unsigned)__builtin_amdgcn_s_getreg((3 << 11) | 20) & 0xFu; }
; __device__ __forceinline__ XcdBarrier xcd_barrier_post(unsigned* bar, volatile LAS unsigned* st) {
;     XcdBarrier b; b.bar = bar; b.x = xb_xcc_id(); b.st = st;
;     if (threadIdx.x == 0) (void)xb_add(&bar[XB_XCNT(b.x)], 1u);
;     return b;
; }
; __global__ void __launch_bounds__(NTHR, 2) fwd_megakernel(Args args) {
;     ...
;     if (threadIdx.x < 2) ((volatile LAS unsigned*)((LAS unsigned char*)lds_raw + LDS_BAR_OFF))[threadIdx.x] = 0u;
;     __syncthreads();
;     (void)xcd_barrier_post((unsigned*)(args.ws + WS_CTL), (volatile LAS unsigned*)((LAS unsigned char*)lds_raw + LDS_BAR_OFF));
_Z14fwd_megakernel4Args:
	s_load_dwordx2 s[46:47], s[0:1], 0xc8
	s_load_dword s94, s[0:1], 0xd0
	s_add_u32 s16, s0, 0xc8
	v_and_b32_e32 v234, 0x3ff, v0
	s_addc_u32 s17, s1, 0
	v_cmp_gt_u32_e32 vcc, 3, v234
	s_and_saveexec_b64 s[4:5], vcc
	v_lshl_add_u32 v1, v234, 2, 0
	v_add_u32_e32 v1, 0x23f00, v1
	v_mov_b32_e32 v2, 0
	ds_write_b32 v1, v2
	s_or_b64 exec, exec, s[4:5]
	s_load_dwordx2 s[8:9], s[0:1], 0xc0
	s_waitcnt lgkmcnt(0)
	s_barrier
	s_getreg_b32 s3, hwreg(HW_REG_XCC_ID, 0, 4)
	s_mov_b32 s20, 0
	v_cmp_eq_u32_e64 s[4:5], 0, v234
	v_mov_b64_e32 v[6:7], s[8:9]
	s_and_saveexec_b64 s[6:7], s[4:5]
	s_cbranch_execz .LBB0_6
	s_mov_b64 s[12:13], exec
	v_mbcnt_lo_u32_b32 v1, s12, 0
	v_mbcnt_hi_u32_b32 v1, s13, v1
	v_cmp_eq_u32_e32 vcc, 0, v1
	v_mov_b64_e32 v[6:7], s[8:9]
	s_and_saveexec_b64 s[10:11], vcc
	s_cbranch_execz .LBB0_5
	s_lshl_b32 s3, s3, 8
	s_and_b32 s3, s3, 0xf00
	s_add_u32 s8, s8, s3
	s_addc_u32 s9, s9, 0
	s_bcnt1_i32_b64 s3, s[12:13]
	v_mov_b32_e32 v1, 0x25d00000
	v_mov_b32_e32 v2, s3
	global_atomic_add v1, v2, s[8:9] offset:1024
	s_load_dwordx2 s[8:9], s[0:1], 0xc0
	s_waitcnt lgkmcnt(0)
	v_mov_b64_e32 v[6:7], s[8:9]

; #define LAS __attribute__((address_space(3)))
; __device__ __forceinline__ void convert_matrix(const Ctx& C, const float* W, int K, int N, bf16* WT, int mode, const float* gs) {
;     LAS float* scr = (LAS float*)(C.lds + C.wave * 16384);
;     const int gw = C.bid * 8 + C.wave, NGW = C.G * 8;
;     const int nblk = N / 32, nitems = (K / 64) * nblk;
;     for (int it = gw; it < nitems; it += NGW) {
;         const int kb = it / nblk, nb = it % nblk, n0 = nb * 32;
;         int drow0 = n0;
;         if (mode == 1) { const int j = n0 < DFF ? n0 : n0 - DFF; drow0 = 256 * (j >> 7) + (j & 127) + (n0 < DFF ? 0 : 128); }
;         transpose_item(W, K, N, WT, kb * 64, n0, drow0, scr, C.lane, gs, mode);
.LBB0_6:
	s_or_b64 exec, exec, s[6:7]
	v_mov_b32_e32 v10, v234
	s_ashr_i32 s21, s20, 31
	v_readfirstlane_b32 s3, v10
	s_ashr_i32 s3, s3, 6
	s_lshl_b64 s[6:7], s[20:21], 3
	s_add_u32 s22, s0, s6
	s_addc_u32 s23, s1, s7
	s_lshl_b32 s19, s3, 14
	s_lshl_b32 s6, s2, 3
	s_add_i32 s33, s19, 0
	s_add_i32 s18, s3, s6
	s_lshl_b32 s44, s46, 3
	v_and_b32_e32 v1, 63, v10
	s_cmpk_lt_i32 s18, 0x1620
	v_lshl_add_u64 v[14:15], v[6:7], 0, s[20:21]
	s_cselect_b64 s[28:29], -1, 0
	s_cmpk_gt_i32 s18, 0x161f
	v_lshrrev_b32_e32 v12, 5, v1
	v_lshrrev_b32_e32 v9, 3, v1
	v_lshlrev_b32_e32 v8, 3, v1
	v_lshlrev_b32_e32 v13, 2, v10
	v_writelane_b32 v254, s6, 0
	s_load_dwordx4 s[24:27], s[0:1], 0x10
	s_load_dwordx2 s[28:29], s[0:1], 0x68
	s_load_dwordx4 s[36:39], s[0:1], 0x70
	s_load_dwordx2 s[30:31], s[0:1], 0x90
	s_load_dwordx4 s[40:43], s[0:1], 0x98
	s_load_dwordx2 s[34:35], s[0:1], 0xa8
	s_load_dwordx2 s[48:49], s[0:1], 0xc0
	s_load_dwordx4 s[64:67], s[0:1], 0x0
	s_mov_b32 s58, s18
	v_and_b32_e32 v1, 63, v234
	v_lshrrev_b32_e32 v6, 5, v1
	v_and_b32_e32 v7, 31, v1
	v_lshlrev_b32_e32 v7, 2, v7
	v_mul_u32_u24_e32 v2, 0x84, v6
	v_add3_u32 v2, s33, v2, v7
	v_and_b32_e32 v4, 7, v1
	v_lshrrev_b32_e32 v8, 3, v1
	v_mul_u32_u24_e32 v3, 0x420, v4
	v_lshlrev_b32_e32 v108, 2, v8
	v_add3_u32 v3, s33, v3, v108
	v_lshlrev_b32_e32 v5, 5, v4
	v_lshlrev_b32_e32 v4, 4, v4
	v_mov_b32_e32 v10, 0
	s_waitcnt lgkmcnt(0)
	s_getreg_b32 s6, hwreg(HW_REG_XCC_ID, 0, 4)
	s_add_u32 s6, s6, 1
	s_add_u32 s8, s48, 0x25d04000
	s_addc_u32 s9, s49, 0
	s_lshl_b32 s7, s2, 2
	v_mov_b32_e32 v11, s7
	v_mov_b32_e32 v12, s6
	global_store_dword v11, v12, s[8:9]
	s_mov_b32 s6, s58
	s_mov_b32 s7, 0
	s_cmp_lt_u32 s58, 26912
	s_cbranch_scc1 .Lp0_lay0_a
	s_sub_u32 s6, s58, 26912
	s_mov_b32 s7, 1

; __device__ __forceinline__ unsigned xb_ld(unsigned* p)              { return __hip_atomic_load(p, __ATOMIC_RELAXED, __HIP_MEMORY_SCOPE_AGENT); }
; __device__ __forceinline__ unsigned xb_add(unsigned* p, unsigned v) { return __hip_atomic_fetch_add(p, v, __ATOMIC_RELAXED, __HIP_MEMORY_SCOPE_AGENT); }
; #define XB_SPIN(cond, bar) do { unsigned _sp = 0; while (cond) { __builtin_amdgcn_s_sleep(1); \
;     if ((++_sp & 255u) == 0u) { if (xb_ld(&(bar)[XB_TMO])) break; if (_sp > XB_SPIN_CAP) { atomicAdd(&(bar)[XB_TMO], 1u); break; } } } } while (0)
; __device__ __forceinline__ void xcd_barrier(const XcdBarrier& b) {
;     asm volatile("s_waitcnt vmcnt(0)" ::: "memory");
;     __syncthreads();
;     if (threadIdx.x == 0) {
;         unsigned* bar = b.bar;
;         __builtin_amdgcn_s_waitcnt(0);
;         unsigned nloc = b.st[0], nx = b.st[1];
;         if (nloc == 0u) { xcd_barrier_complete(bar, b.x, nloc, nx); b.st[0] = nloc; b.st[1] = nx; }
;         const unsigned old = xb_add(&bar[XB_XSUB(b.x)], 1u);
;         const unsigned gen = old / nloc;
;         if (old + 1u == (gen + 1u) * nloc) {
;             __builtin_amdgcn_fence(__ATOMIC_RELEASE, "agent");
;             asm volatile("s_waitcnt vmcnt(0)" ::: "memory");
;             const unsigned og = xb_add(&bar[XB_TOP], 1u);
;             const unsigned tg = og / nx;
;             if (og + 1u == (tg + 1u) * nx) xb_add(&bar[XB_TOPGEN], 1u);
;             else XB_SPIN(xb_ld(&bar[XB_TOPGEN]) == tg, bar);
;             __builtin_amdgcn_fence(__ATOMIC_ACQUIRE, "agent");
;             xb_add(&bar[XB_XGEN(b.x)], 1u);
;             asm volatile("s_waitcnt vmcnt(0)" ::: "memory");
;         } else {
;             XB_SPIN(xb_ld(&bar[XB_XGEN(b.x)]) == gen, bar);
;             __builtin_amdgcn_fence(__ATOMIC_ACQUIRE, "agent");
;             asm volatile("s_waitcnt vmcnt(0)" ::: "memory");
;         }
;     }
;     __syncthreads();
; }
.LBB0_907:
	s_mov_b32 s14, 0
	s_getreg_b32 s16, hwreg(HW_REG_XCC_ID, 0, 4)
	s_waitcnt vmcnt(0)
	s_waitcnt lgkmcnt(0)
	s_barrier
	s_and_saveexec_b64 s[10:11], s[4:5]
	s_cbranch_execz .LBB0_959
	v_mov_b32_e32 v0, 0x23f08
	ds_read_b32 v1, v0
	s_load_dwordx2 s[14:15], s[0:1], 0xc0
	s_waitcnt lgkmcnt(0)
	v_readfirstlane_b32 s16, v1
	s_cmp_eq_u32 s16, 1
	s_cbranch_scc1 .Llb_go_6
	s_cmp_eq_u32 s16, 2
	s_cbranch_scc1 .Llb_full_6
	s_mov_b64 s[18:19], exec
	s_mov_b64 exec, -1
	s_add_u32 s20, s14, 0x25d04000
	s_addc_u32 s21, s15, 0
	v_and_b32_e32 v2, 63, v234
	v_lshlrev_b32_e32 v3, 2, v2
	v_and_b32_e32 v9, 7, v2
	v_lshlrev_b32_e32 v9, 2, v9
	global_load_dword v4, v3, s[20:21] sc1
	global_load_dword v5, v3, s[20:21] offset:256 sc1
	global_load_dword v6, v3, s[20:21] offset:512 sc1
	global_load_dword v7, v3, s[20:21] offset:768 sc1
	global_load_dword v8, v9, s[20:21] sc1
	s_waitcnt vmcnt(0)
	v_cmp_eq_u32_e32 vcc, v4, v8
	s_mov_b64 s[24:25], vcc
	v_cmp_eq_u32_e32 vcc, v5, v8
	s_and_b64 s[24:25], s[24:25], vcc
	v_cmp_eq_u32_e32 vcc, v6, v8
	s_and_b64 s[24:25], s[24:25], vcc
	v_cmp_eq_u32_e32 vcc, v7, v8
	s_and_b64 s[24:25], s[24:25], vcc
	v_cmp_ne_u32_e32 vcc, 0, v8
	s_and_b64 s[24:25], s[24:25], vcc
	s_mov_b32 s16, 2
	s_cmp_eq_u64 s[24:25], exec
	s_cbranch_scc0 .Llb_dec_6
	s_cmpk_eq_i32 s46, 0x100
	s_cbranch_scc0 .Llb_dec_6
	s_mov_b32 s16, 1
.Llb_dec_6:
	s_mov_b64 exec, s[18:19]
	v_mov_b32_e32 v1, s16
	ds_write_b32 v0, v1
	s_waitcnt lgkmcnt(0)
	s_cmp_eq_u32 s16, 1
	s_cbranch_scc0 .Llb_full_6
.Llb_go_6:
	s_and_b32 s16, s2, 7
	s_lshl_b32 s16, s16, 8
	s_add_u32 s20, s14, 0x25d05000
	s_addc_u32 s21, s15, 0
	s_add_u32 s20, s20, s16
	s_addc_u32 s21, s21, 0
	v_mov_b32_e32 v2, 0
	v_mov_b32_e32 v3, 1
	global_atomic_add v4, v2, v3, s[20:21] sc0
	s_waitcnt vmcnt(0)
	v_readfirstlane_b32 s17, v4
	s_lshr_b32 s22, s17, 5
	s_add_u32 s17, s17, 1
	s_and_b32 s17, s17, 31
	s_cmp_eq_u32 s17, 0
	s_cbranch_scc0 .Llb_wait_6
	global_atomic_add v2, v3, s[20:21] offset:2048
	s_branch .Llb_acq_6
.Llb_wait_6:
	s_mov_b32 s23, 0
.Llb_spin_6:
	s_sleep 1
	global_load_dword v4, v2, s[20:21] offset:2048 sc1
	s_waitcnt vmcnt(0)
	v_readfirstlane_b32 s24, v4
	s_cmp_lg_u32 s24, s22
	s_cbranch_scc1 .Llb_acq_6
	s_add_u32 s23, s23, 1
	s_cmp_lt_u32 s23, 0x100000
	s_cbranch_scc1 .Llb_spin_6
.Llb_acq_6:
	s_waitcnt vmcnt(0)
	buffer_inv sc1
	s_waitcnt vmcnt(0)
	s_branch .LBB0_959
.Llb_full_6:
	s_ashr_i32 s15, s14, 31
	s_lshl_b64 s[18:19], s[14:15], 2
	s_add_u32 s12, s12, s18
	s_addc_u32 s13, s13, s19
	s_add_u32 s12, s12, 0x25d00000
	s_addc_u32 s13, s13, 0
	s_add_i32 s29, s14, 0
	s_add_i32 s29, s29, 0x23f00
	v_mov_b32_e32 v0, s29
	s_waitcnt vmcnt(0) expcnt(0) lgkmcnt(0)
	ds_read_b32 v2, v0
	ds_read_b32 v0, v0 offset:4
	s_and_b32 s28, s16, 15
	s_waitcnt lgkmcnt(1)
	v_cmp_ne_u32_e32 vcc, 0, v2
	s_cbranch_vccnz .LBB0_923
	s_add_u32 s14, s12, 0x1000
	s_addc_u32 s15, s13, 0
	s_add_u32 s16, s12, 0x1100
	s_addc_u32 s17, s13, 0
	s_add_u32 s18, s12, 0x1200
	s_addc_u32 s19, s13, 0
	s_mul_i32 s30, s47, s94
	s_add_u32 s20, s12, 0x1300
	s_mul_i32 s30, s30, s46
	s_addc_u32 s21, s13, 0
	s_mov_b32 s31, 1
	v_mov_b32_e32 v16, 0
	s_branch .LBB0_911

; __device__ __forceinline__ unsigned xb_add(unsigned* p, unsigned v) { return __hip_atomic_fetch_add(p, v, __ATOMIC_RELAXED, __HIP_MEMORY_SCOPE_AGENT); }
; __device__ __forceinline__ void xcd_barrier(const XcdBarrier& b) {
;     asm volatile("s_waitcnt vmcnt(0)" ::: "memory");
;     __syncthreads();
;     if (threadIdx.x == 0) {
;         unsigned* bar = b.bar;
;         __builtin_amdgcn_s_waitcnt(0);
;         unsigned nloc = b.st[0], nx = b.st[1];
;         if (nloc == 0u) { xcd_barrier_complete(bar, b.x, nloc, nx); b.st[0] = nloc; b.st[1] = nx; }
;         const unsigned old = xb_add(&bar[XB_XSUB(b.x)], 1u);
.LBB0_1176:
	s_mov_b32 s16, 0
	s_getreg_b32 s10, hwreg(HW_REG_XCC_ID, 0, 4)
	s_waitcnt vmcnt(0)
	s_waitcnt lgkmcnt(0)
	s_barrier
	s_and_saveexec_b64 s[12:13], s[4:5]
	s_cbranch_execz .LBB0_1228
	v_mov_b32_e32 v0, 0x23f08
	ds_read_b32 v1, v0
	s_load_dwordx2 s[14:15], s[0:1], 0xc0
	s_waitcnt lgkmcnt(0)
	v_readfirstlane_b32 s16, v1
	s_cmp_eq_u32 s16, 1
	s_cbranch_scc1 .Llb_go_9
	s_cmp_eq_u32 s16, 2
	s_cbranch_scc1 .Llb_full_9
	s_mov_b64 s[18:19], exec
	s_mov_b64 exec, -1
	s_add_u32 s20, s14, 0x25d04000
	s_addc_u32 s21, s15, 0
	v_and_b32_e32 v2, 63, v234
	v_lshlrev_b32_e32 v3, 2, v2
	v_and_b32_e32 v9, 7, v2
	v_lshlrev_b32_e32 v9, 2, v9
	global_load_dword v4, v3, s[20:21] sc1
	global_load_dword v5, v3, s[20:21] offset:256 sc1
	global_load_dword v6, v3, s[20:21] offset:512 sc1
	global_load_dword v7, v3, s[20:21] offset:768 sc1
	global_load_dword v8, v9, s[20:21] sc1
	s_waitcnt vmcnt(0)
	v_cmp_eq_u32_e32 vcc, v4, v8
	s_mov_b64 s[24:25], vcc
	v_cmp_eq_u32_e32 vcc, v5, v8
	s_and_b64 s[24:25], s[24:25], vcc
	v_cmp_eq_u32_e32 vcc, v6, v8
	s_and_b64 s[24:25], s[24:25], vcc
	v_cmp_eq_u32_e32 vcc, v7, v8
	s_and_b64 s[24:25], s[24:25], vcc
	v_cmp_ne_u32_e32 vcc, 0, v8
	s_and_b64 s[24:25], s[24:25], vcc
	s_mov_b32 s16, 2
	s_cmp_eq_u64 s[24:25], exec
	s_cbranch_scc0 .Llb_dec_9
	s_cmpk_eq_i32 s46, 0x100
	s_cbranch_scc0 .Llb_dec_9
	s_mov_b32 s16, 1

; __device__ __forceinline__ unsigned xb_ld(unsigned* p)              { return __hip_atomic_load(p, __ATOMIC_RELAXED, __HIP_MEMORY_SCOPE_AGENT); }
; __device__ __forceinline__ unsigned xb_add(unsigned* p, unsigned v) { return __hip_atomic_fetch_add(p, v, __ATOMIC_RELAXED, __HIP_MEMORY_SCOPE_AGENT); }
; __device__ __forceinline__ void xcd_barrier_complete(unsigned* bar, unsigned x, unsigned& nloc, unsigned& nx) {
;     const unsigned G = gridDim.x * gridDim.y * gridDim.z;
;     unsigned sum, cnt, mine, sp = 0u;
;     for (;;) {
;         sum = 0u; cnt = 0u; mine = 0u;
; #pragma unroll
;         for (unsigned j = 0; j < 16; ++j) { const unsigned c = xb_ld(&bar[XB_XCNT(j)]); sum += c; cnt += (c > 0u) ? 1u : 0u; mine = (j == x) ? c : mine; }
; __device__ __forceinline__ void xcd_barrier(const XcdBarrier& b) {
;     asm volatile("s_waitcnt vmcnt(0)" ::: "memory");
;     __syncthreads();
;     if (threadIdx.x == 0) {
;         unsigned* bar = b.bar;
;         __builtin_amdgcn_s_waitcnt(0);
;         unsigned nloc = b.st[0], nx = b.st[1];
;         if (nloc == 0u) { xcd_barrier_complete(bar, b.x, nloc, nx); b.st[0] = nloc; b.st[1] = nx; }
;         const unsigned old = xb_add(&bar[XB_XSUB(b.x)], 1u);
.Llb_full_9:
	s_load_dwordx2 s[14:15], s[0:1], 0xc0
	s_ashr_i32 s17, s16, 31
	s_lshl_b64 s[18:19], s[16:17], 2
	s_waitcnt vmcnt(0) expcnt(0) lgkmcnt(0)
	s_add_u32 s11, s14, s18
	s_addc_u32 s15, s15, s19
	s_add_u32 s14, s11, 0x25d00000
	s_addc_u32 s15, s15, 0
	s_add_i32 s11, s16, 0
	s_add_i32 s11, s11, 0x23f00
	v_mov_b32_e32 v0, s11
	ds_read_b32 v2, v0
	ds_read_b32 v0, v0 offset:4
	s_and_b32 s10, s10, 15
	s_waitcnt lgkmcnt(1)
	v_cmp_ne_u32_e32 vcc, 0, v2
	s_cbranch_vccnz .LBB0_1192
	s_add_u32 s16, s14, 0x1000
	s_addc_u32 s17, s15, 0
	s_add_u32 s18, s14, 0x1100
	s_addc_u32 s19, s15, 0
	s_add_u32 s20, s14, 0x1200
	s_addc_u32 s21, s15, 0
	s_mul_i32 s30, s47, s94
	s_add_u32 s22, s14, 0x1300
	s_mul_i32 s30, s30, s46
	s_addc_u32 s23, s15, 0
	s_mov_b32 s31, 1
	v_mov_b32_e32 v16, 0
	s_branch .LBB0_1180

; __device__ __forceinline__ unsigned xb_add(unsigned* p, unsigned v) { return __hip_atomic_fetch_add(p, v, __ATOMIC_RELAXED, __HIP_MEMORY_SCOPE_AGENT); }
; __device__ __forceinline__ void xcd_barrier(const XcdBarrier& b) {
;     asm volatile("s_waitcnt vmcnt(0)" ::: "memory");
;     __syncthreads();
;     if (threadIdx.x == 0) {
;         unsigned* bar = b.bar;
;         __builtin_amdgcn_s_waitcnt(0);
;         unsigned nloc = b.st[0], nx = b.st[1];
;         if (nloc == 0u) { xcd_barrier_complete(bar, b.x, nloc, nx); b.st[0] = nloc; b.st[1] = nx; }
;         const unsigned old = xb_add(&bar[XB_XSUB(b.x)], 1u);
.LBB0_1995:
	s_mov_b32 s16, 0
	s_getreg_b32 s10, hwreg(HW_REG_XCC_ID, 0, 4)
	s_waitcnt vmcnt(0)
	s_waitcnt lgkmcnt(0)
	s_barrier
	s_and_saveexec_b64 s[8:9], s[4:5]
	s_cbranch_execz .LBB0_2047
	v_mov_b32_e32 v0, 0x23f08
	ds_read_b32 v1, v0
	s_load_dwordx2 s[14:15], s[0:1], 0xc0
	s_waitcnt lgkmcnt(0)
	v_readfirstlane_b32 s16, v1
	s_cmp_eq_u32 s16, 1
	s_cbranch_scc1 .Llb_go_15
	s_cmp_eq_u32 s16, 2
	s_cbranch_scc1 .Llb_full_15
	s_mov_b64 s[18:19], exec
	s_mov_b64 exec, -1
	s_add_u32 s20, s14, 0x25d04000
	s_addc_u32 s21, s15, 0
	v_and_b32_e32 v2, 63, v234
	v_lshlrev_b32_e32 v3, 2, v2
	v_and_b32_e32 v9, 7, v2
	v_lshlrev_b32_e32 v9, 2, v9
	global_load_dword v4, v3, s[20:21] sc1
	global_load_dword v5, v3, s[20:21] offset:256 sc1
	global_load_dword v6, v3, s[20:21] offset:512 sc1
	global_load_dword v7, v3, s[20:21] offset:768 sc1
	global_load_dword v8, v9, s[20:21] sc1
	s_waitcnt vmcnt(0)
	v_cmp_eq_u32_e32 vcc, v4, v8
	s_mov_b64 s[24:25], vcc
	v_cmp_eq_u32_e32 vcc, v5, v8
	s_and_b64 s[24:25], s[24:25], vcc
	v_cmp_eq_u32_e32 vcc, v6, v8
	s_and_b64 s[24:25], s[24:25], vcc
	v_cmp_eq_u32_e32 vcc, v7, v8
	s_and_b64 s[24:25], s[24:25], vcc
	v_cmp_ne_u32_e32 vcc, 0, v8
	s_and_b64 s[24:25], s[24:25], vcc
	s_mov_b32 s16, 2
	s_cmp_eq_u64 s[24:25], exec
	s_cbranch_scc0 .Llb_dec_15
	s_cmpk_eq_i32 s46, 0x100
	s_cbranch_scc0 .Llb_dec_15
	s_mov_b32 s16, 1

; __device__ __forceinline__ unsigned xb_ld(unsigned* p)              { return __hip_atomic_load(p, __ATOMIC_RELAXED, __HIP_MEMORY_SCOPE_AGENT); }
; __device__ __forceinline__ unsigned xb_add(unsigned* p, unsigned v) { return __hip_atomic_fetch_add(p, v, __ATOMIC_RELAXED, __HIP_MEMORY_SCOPE_AGENT); }
; __device__ __forceinline__ void xcd_barrier_complete(unsigned* bar, unsigned x, unsigned& nloc, unsigned& nx) {
;     const unsigned G = gridDim.x * gridDim.y * gridDim.z;
;     unsigned sum, cnt, mine, sp = 0u;
;     for (;;) {
;         sum = 0u; cnt = 0u; mine = 0u;
; #pragma unroll
;         for (unsigned j = 0; j < 16; ++j) { const unsigned c = xb_ld(&bar[XB_XCNT(j)]); sum += c; cnt += (c > 0u) ? 1u : 0u; mine = (j == x) ? c : mine; }
; __device__ __forceinline__ void xcd_barrier(const XcdBarrier& b) {
;     asm volatile("s_waitcnt vmcnt(0)" ::: "memory");
;     __syncthreads();
;     if (threadIdx.x == 0) {
;         unsigned* bar = b.bar;
;         __builtin_amdgcn_s_waitcnt(0);
;         unsigned nloc = b.st[0], nx = b.st[1];
;         if (nloc == 0u) { xcd_barrier_complete(bar, b.x, nloc, nx); b.st[0] = nloc; b.st[1] = nx; }
;         const unsigned old = xb_add(&bar[XB_XSUB(b.x)], 1u);
.Llb_full_15:
	s_ashr_i32 s17, s16, 31
	s_lshl_b64 s[12:13], s[16:17], 2
	s_add_u32 s11, s14, s12
	s_addc_u32 s13, s15, s13
	s_add_u32 s12, s11, 0x25d00000
	s_addc_u32 s13, s13, 0
	s_add_i32 s11, s16, 0
	s_add_i32 s11, s11, 0x23f00
	v_mov_b32_e32 v0, s11
	s_waitcnt vmcnt(0) expcnt(0) lgkmcnt(0)
	ds_read_b32 v2, v0
	ds_read_b32 v0, v0 offset:4
	s_and_b32 s10, s10, 15
	s_waitcnt lgkmcnt(1)
	v_cmp_ne_u32_e32 vcc, 0, v2
	s_cbranch_vccnz .LBB0_2011
	s_add_u32 s14, s12, 0x1000
	s_addc_u32 s15, s13, 0
	s_add_u32 s16, s12, 0x1100
	s_addc_u32 s17, s13, 0
	s_add_u32 s18, s12, 0x1200
	s_addc_u32 s19, s13, 0
	s_mul_i32 s28, s47, s94
	s_add_u32 s20, s12, 0x1300
	s_mul_i32 s28, s28, s46
	s_addc_u32 s21, s13, 0
	s_mov_b32 s29, 1
	v_mov_b32_e32 v16, 0
	s_branch .LBB0_1999

; __device__ __forceinline__ unsigned xb_add(unsigned* p, unsigned v) { return __hip_atomic_fetch_add(p, v, __ATOMIC_RELAXED, __HIP_MEMORY_SCOPE_AGENT); }
; __device__ __forceinline__ void xcd_barrier(const XcdBarrier& b) {
;     asm volatile("s_waitcnt vmcnt(0)" ::: "memory");
;     __syncthreads();
;     if (threadIdx.x == 0) {
;         unsigned* bar = b.bar;
;         __builtin_amdgcn_s_waitcnt(0);
;         unsigned nloc = b.st[0], nx = b.st[1];
;         if (nloc == 0u) { xcd_barrier_complete(bar, b.x, nloc, nx); b.st[0] = nloc; b.st[1] = nx; }
;         const unsigned old = xb_add(&bar[XB_XSUB(b.x)], 1u);
.LBB0_2264:
	s_mov_b32 s12, 0
	s_getreg_b32 s14, hwreg(HW_REG_XCC_ID, 0, 4)
	s_waitcnt vmcnt(0)
	s_waitcnt lgkmcnt(0)
	s_barrier
	s_and_saveexec_b64 s[8:9], s[4:5]
	s_cbranch_execz .LBB0_2316
	v_mov_b32_e32 v0, 0x23f08
	ds_read_b32 v1, v0
	s_load_dwordx2 s[14:15], s[0:1], 0xc0
	s_waitcnt lgkmcnt(0)
	v_readfirstlane_b32 s16, v1
	s_cmp_eq_u32 s16, 1
	s_cbranch_scc1 .Llb_go_18
	s_cmp_eq_u32 s16, 2
	s_cbranch_scc1 .Llb_full_18
	s_mov_b64 s[18:19], exec
	s_mov_b64 exec, -1
	s_add_u32 s20, s14, 0x25d04000
	s_addc_u32 s21, s15, 0
	v_and_b32_e32 v2, 63, v234
	v_lshlrev_b32_e32 v3, 2, v2
	v_and_b32_e32 v9, 7, v2
	v_lshlrev_b32_e32 v9, 2, v9
	global_load_dword v4, v3, s[20:21] sc1
	global_load_dword v5, v3, s[20:21] offset:256 sc1
	global_load_dword v6, v3, s[20:21] offset:512 sc1
	global_load_dword v7, v3, s[20:21] offset:768 sc1
	global_load_dword v8, v9, s[20:21] sc1
	s_waitcnt vmcnt(0)
	v_cmp_eq_u32_e32 vcc, v4, v8
	s_mov_b64 s[24:25], vcc
	v_cmp_eq_u32_e32 vcc, v5, v8
	s_and_b64 s[24:25], s[24:25], vcc
	v_cmp_eq_u32_e32 vcc, v6, v8
	s_and_b64 s[24:25], s[24:25], vcc
	v_cmp_eq_u32_e32 vcc, v7, v8
	s_and_b64 s[24:25], s[24:25], vcc
	v_cmp_ne_u32_e32 vcc, 0, v8
	s_and_b64 s[24:25], s[24:25], vcc
	s_mov_b32 s16, 2
	s_cmp_eq_u64 s[24:25], exec
	s_cbranch_scc0 .Llb_dec_18
	s_cmpk_eq_i32 s46, 0x100
	s_cbranch_scc0 .Llb_dec_18
	s_mov_b32 s16, 1

; __device__ __forceinline__ unsigned xb_ld(unsigned* p)              { return __hip_atomic_load(p, __ATOMIC_RELAXED, __HIP_MEMORY_SCOPE_AGENT); }
; __device__ __forceinline__ unsigned xb_add(unsigned* p, unsigned v) { return __hip_atomic_fetch_add(p, v, __ATOMIC_RELAXED, __HIP_MEMORY_SCOPE_AGENT); }
; __device__ __forceinline__ void xcd_barrier_complete(unsigned* bar, unsigned x, unsigned& nloc, unsigned& nx) {
;     const unsigned G = gridDim.x * gridDim.y * gridDim.z;
;     unsigned sum, cnt, mine, sp = 0u;
;     for (;;) {
;         sum = 0u; cnt = 0u; mine = 0u;
; #pragma unroll
;         for (unsigned j = 0; j < 16; ++j) { const unsigned c = xb_ld(&bar[XB_XCNT(j)]); sum += c; cnt += (c > 0u) ? 1u : 0u; mine = (j == x) ? c : mine; }
; __device__ __forceinline__ void xcd_barrier(const XcdBarrier& b) {
;     asm volatile("s_waitcnt vmcnt(0)" ::: "memory");
;     __syncthreads();
;     if (threadIdx.x == 0) {
;         unsigned* bar = b.bar;
;         __builtin_amdgcn_s_waitcnt(0);
;         unsigned nloc = b.st[0], nx = b.st[1];
;         if (nloc == 0u) { xcd_barrier_complete(bar, b.x, nloc, nx); b.st[0] = nloc; b.st[1] = nx; }
;         const unsigned old = xb_add(&bar[XB_XSUB(b.x)], 1u);
.Llb_full_18:
	s_ashr_i32 s13, s12, 31
	s_lshl_b64 s[16:17], s[12:13], 2
	s_add_u32 s10, s10, s16
	s_addc_u32 s11, s11, s17
	s_add_u32 s10, s10, 0x25d00000
	s_addc_u32 s11, s11, 0
	s_add_i32 s27, s12, 0
	s_add_i32 s27, s27, 0x23f00
	v_mov_b32_e32 v0, s27
	s_waitcnt vmcnt(0) expcnt(0) lgkmcnt(0)
	ds_read_b32 v2, v0
	ds_read_b32 v0, v0 offset:4
	s_and_b32 s26, s14, 15
	s_waitcnt lgkmcnt(1)
	v_cmp_ne_u32_e32 vcc, 0, v2
	s_cbranch_vccnz .LBB0_2280
	s_add_u32 s12, s10, 0x1000
	s_addc_u32 s13, s11, 0
	s_add_u32 s14, s10, 0x1100
	s_addc_u32 s15, s11, 0
	s_add_u32 s16, s10, 0x1200
	s_addc_u32 s17, s11, 0
	s_mul_i32 s28, s47, s94
	s_add_u32 s18, s10, 0x1300
	s_mul_i32 s28, s28, s46
	s_addc_u32 s19, s11, 0
	s_mov_b32 s29, 1
	v_mov_b32_e32 v16, 0
	s_branch .LBB0_2268
